# all 176 WD0 transposes run at the start of GU0 on workgroups 128..255 (one or two items each); ATT0 hosts only WO0 and WGU0 (items 192..607)
# baseline (speedup 1.0000x reference)
.LBB0_629:
	s_or_b64 exec, exec, s[4:5]
	s_cmpk_lt_i32 s78, 0x580
	s_cselect_b64 s[0:1], -1, 0
	v_writelane_b32 v219, s0, 52
	s_cmpk_gt_i32 s78, 0x57f
	v_readfirstlane_b32 s4, v168
	s_waitcnt lgkmcnt(0)
	s_barrier
	v_mov_b32_e32 v222, 0
	v_writelane_b32 v219, s1, 53
	v_readlane_b32 s78, v219, 30
	s_nop 3
	s_cmpk_lt_u32 s78, 0x80
	s_cbranch_scc1 .Lgu0e_skip
	v_writelane_b32 v220, s0, 0
	v_writelane_b32 v220, s1, 1
	v_writelane_b32 v220, s2, 2
	v_writelane_b32 v220, s3, 3
	v_writelane_b32 v220, s4, 4
	v_writelane_b32 v220, s5, 5
	v_writelane_b32 v220, s6, 6
	v_writelane_b32 v220, s7, 7
	v_writelane_b32 v220, s8, 8
	v_writelane_b32 v220, s9, 9
	v_writelane_b32 v220, s10, 10
	v_writelane_b32 v220, s11, 11
	v_writelane_b32 v220, s12, 12
	v_writelane_b32 v220, s13, 13
	v_writelane_b32 v220, s14, 14
	v_writelane_b32 v220, s15, 15
	v_writelane_b32 v220, s16, 16
	v_writelane_b32 v220, s17, 17
	v_writelane_b32 v220, s18, 18
	v_writelane_b32 v220, s19, 19
	v_writelane_b32 v220, s20, 20
	v_writelane_b32 v220, s21, 21
	v_writelane_b32 v220, s22, 22
	v_writelane_b32 v220, s23, 23
	v_writelane_b32 v220, s24, 24
	v_writelane_b32 v220, s25, 25
	v_writelane_b32 v220, s26, 26
	v_writelane_b32 v220, s27, 27
	v_writelane_b32 v220, s36, 28
	v_writelane_b32 v220, s37, 29
	v_writelane_b32 v220, s38, 30
	v_writelane_b32 v220, s39, 31
	v_writelane_b32 v220, s40, 32
	v_writelane_b32 v220, s41, 33
	v_writelane_b32 v220, s42, 34
	v_writelane_b32 v220, s43, 35
	v_writelane_b32 v220, s44, 36
	v_writelane_b32 v220, s45, 37
	v_writelane_b32 v220, s46, 38
	v_writelane_b32 v220, s47, 39
	v_writelane_b32 v220, s48, 40
	v_writelane_b32 v220, s49, 41
	v_writelane_b32 v220, s50, 42
	v_writelane_b32 v220, s51, 43
	s_cmpk_gt_i32 s78, 0x17f
	s_waitcnt vmcnt(0) lgkmcnt(0)
	s_barrier
	s_cbranch_scc1 .Lgu0e_BB0_1034
	s_movk_i32 s1, 0x2100
	v_and_b32_e32 v4, 56, v144
	v_mad_u32_u24 v1, v148, s1, 0
	v_lshrrev_b32_e32 v0, 5, v149
	v_and_b32_e32 v2, 31, v168
	v_mul_u32_u24_e32 v3, 0x84, v4
	v_lshlrev_b32_e32 v7, 2, v185
	s_add_i32 s0, s78, 0x1e0
	v_mov_b32_e32 v5, 0
	v_lshl_add_u32 v6, v2, 2, v1
	s_movk_i32 s1, 0x84
	v_add3_u32 v20, v1, v3, v7
	v_or_b32_e32 v21, 8, v185
	v_or_b32_e32 v22, 16, v185
	v_or_b32_e32 v23, 24, v185
	v_mov_b32_e32 v1, v0
	s_movk_i32 s2, 0x187f
	v_mov_b32_e32 v24, 0xffffe780
	v_mov_b32_e32 v25, 0xc00
	v_mov_b32_e32 v26, 0x600
	s_movk_i32 s3, 0x1ff
	s_movk_i32 s4, 0xcff
	v_lshlrev_b32_e32 v8, 2, v2
	v_lshlrev_b32_e32 v10, 1, v4
	v_mov_b32_e32 v27, 0x2c0000
	v_mov_b32_e32 v28, 0x1400000
	v_mov_b32_e32 v29, 0x2980000
	v_mov_b32_e32 v30, 0x900000
	v_mov_b32_e32 v31, 0x1e80000
	v_mov_b32_e32 v32, 0x700000
	v_mov_b32_e32 v33, 0x1c80000
	v_mov_b32_e32 v34, 0x100000
	v_mov_b32_e32 v35, 0x1980000

.Lgu0e_BB0_1032:
	s_lshl_b32 s8, s6, 1
	s_lshl_b32 s9, s5, 1
	v_or_b32_e32 v9, s8, v1
	v_or_b32_e32 v11, s9, v0
	s_add_i32 s10, s8, 4
	s_add_i32 s11, s9, 4
	s_add_i32 s12, s8, 8
	s_add_i32 s13, s9, 8
	s_add_i32 s14, s8, 12
	s_add_i32 s15, s9, 12
	s_add_i32 s16, s8, 16
	s_add_i32 s17, s9, 16
	s_add_i32 s18, s8, 20
	s_add_i32 s19, s9, 20
	s_add_i32 s20, s8, 24
	s_add_i32 s21, s9, 24
	s_add_i32 s8, s8, 28
	s_add_i32 s9, s9, 28
	v_add_u32_e32 v17, v9, v7
	v_add_u32_e32 v37, v11, v16
	v_or_b32_e32 v70, s10, v1
	v_or_b32_e32 v71, s11, v0
	v_or_b32_e32 v72, s12, v1
	v_or_b32_e32 v73, s13, v0
	v_or_b32_e32 v74, s14, v1
	v_or_b32_e32 v75, s15, v0
	v_or_b32_e32 v76, s16, v1
	v_or_b32_e32 v77, s17, v0
	v_or_b32_e32 v78, s18, v1
	v_or_b32_e32 v79, s19, v0
	v_or_b32_e32 v80, s20, v1
	v_or_b32_e32 v81, s21, v0
	v_or_b32_e32 v82, s8, v1
	v_or_b32_e32 v83, s9, v0
	v_ashrrev_i32_e32 v42, 31, v37
	v_ashrrev_i32_e32 v43, 31, v17
	v_mul_lo_u32 v84, v3, v17
	v_mad_u64_u32 v[38:39], s[8:9], v2, v17, 0
	v_mul_lo_u32 v17, v13, v37
	v_mad_u64_u32 v[40:41], s[8:9], v12, v37, 0
	v_add_u32_e32 v37, v70, v7
	v_add_u32_e32 v44, v71, v16
	v_add_u32_e32 v46, v72, v7
	v_add_u32_e32 v48, v73, v16
	v_add_u32_e32 v50, v74, v7
	v_add_u32_e32 v52, v75, v16
	v_add_u32_e32 v54, v76, v7
	v_add_u32_e32 v56, v77, v16
	v_add_u32_e32 v58, v78, v7
	v_add_u32_e32 v60, v79, v16
	v_add_u32_e32 v62, v80, v7
	v_add_u32_e32 v64, v81, v16
	v_add_u32_e32 v66, v82, v7
	v_add_u32_e32 v68, v83, v16
	v_mul_lo_u32 v85, v2, v43
	v_mul_lo_u32 v86, v12, v42
	v_ashrrev_i32_e32 v87, 31, v44
	v_ashrrev_i32_e32 v88, 31, v37
	v_ashrrev_i32_e32 v90, 31, v48
	v_ashrrev_i32_e32 v91, 31, v46
	v_ashrrev_i32_e32 v94, 31, v52
	v_ashrrev_i32_e32 v95, 31, v50
	v_ashrrev_i32_e32 v98, 31, v56
	v_ashrrev_i32_e32 v99, 31, v54
	v_ashrrev_i32_e32 v102, 31, v60
	v_ashrrev_i32_e32 v103, 31, v58
	v_ashrrev_i32_e32 v106, 31, v64
	v_ashrrev_i32_e32 v107, 31, v62
	v_ashrrev_i32_e32 v110, 31, v68
	v_ashrrev_i32_e32 v111, 31, v66
	v_mul_lo_u32 v89, v3, v37
	v_mad_u64_u32 v[42:43], s[8:9], v2, v37, 0
	v_mul_lo_u32 v37, v13, v44
	v_mad_u64_u32 v[44:45], s[8:9], v12, v44, 0
	v_mul_lo_u32 v92, v3, v46
	v_mad_u64_u32 v[46:47], s[8:9], v2, v46, 0
	v_mul_lo_u32 v93, v13, v48
	v_mad_u64_u32 v[48:49], s[8:9], v12, v48, 0
	v_mul_lo_u32 v96, v3, v50
	v_mad_u64_u32 v[50:51], s[8:9], v2, v50, 0
	v_mul_lo_u32 v97, v13, v52
	v_mad_u64_u32 v[52:53], s[8:9], v12, v52, 0
	v_mul_lo_u32 v100, v3, v54
	v_mad_u64_u32 v[54:55], s[8:9], v2, v54, 0
	v_mul_lo_u32 v101, v13, v56
	v_mad_u64_u32 v[56:57], s[8:9], v12, v56, 0
	v_mul_lo_u32 v104, v3, v58
	v_mad_u64_u32 v[58:59], s[8:9], v2, v58, 0
	v_mul_lo_u32 v105, v13, v60
	v_mad_u64_u32 v[60:61], s[8:9], v12, v60, 0
	v_mul_lo_u32 v108, v3, v62
	v_mad_u64_u32 v[62:63], s[8:9], v2, v62, 0
	v_mul_lo_u32 v109, v13, v64
	v_mad_u64_u32 v[64:65], s[8:9], v12, v64, 0
	v_mul_lo_u32 v112, v3, v66
	v_mad_u64_u32 v[66:67], s[8:9], v2, v66, 0
	v_mul_lo_u32 v113, v13, v68
	v_mad_u64_u32 v[68:69], s[8:9], v12, v68, 0
	v_add3_u32 v39, v39, v85, v84
	v_add3_u32 v41, v41, v86, v17
	v_mul_lo_u32 v17, v2, v88
	v_mul_lo_u32 v84, v12, v87
	v_mul_lo_u32 v85, v2, v91
	v_mul_lo_u32 v86, v12, v90
	v_mul_lo_u32 v87, v2, v95
	v_mul_lo_u32 v88, v12, v94
	v_mul_lo_u32 v90, v2, v99
	v_mul_lo_u32 v91, v12, v98
	v_mul_lo_u32 v94, v2, v103
	v_mul_lo_u32 v95, v12, v102
	v_mul_lo_u32 v98, v2, v107
	v_mul_lo_u32 v99, v12, v106
	v_mul_lo_u32 v102, v2, v111
	v_mul_lo_u32 v103, v12, v110
	v_lshl_add_u64 v[40:41], v[40:41], 2, v[18:19]
	v_add3_u32 v43, v43, v17, v89
	v_add3_u32 v45, v45, v84, v37
	v_add3_u32 v47, v47, v85, v92
	v_add3_u32 v49, v49, v86, v93
	v_add3_u32 v51, v51, v87, v96
	v_add3_u32 v53, v53, v88, v97
	v_add3_u32 v55, v55, v90, v100
	v_add3_u32 v57, v57, v91, v101
	v_add3_u32 v59, v59, v94, v104
	v_add3_u32 v61, v61, v95, v105
	v_add3_u32 v63, v63, v98, v108
	v_add3_u32 v65, v65, v99, v109
	v_add3_u32 v67, v67, v102, v112
	v_add3_u32 v69, v69, v103, v113
	v_lshl_add_u64 v[38:39], v[38:39], 2, v[18:19]
	v_lshl_add_u64 v[44:45], v[44:45], 2, v[18:19]
	v_lshl_add_u64 v[42:43], v[42:43], 2, v[18:19]
	v_lshl_add_u64 v[48:49], v[48:49], 2, v[18:19]
	v_lshl_add_u64 v[46:47], v[46:47], 2, v[18:19]
	v_lshl_add_u64 v[52:53], v[52:53], 2, v[18:19]
	v_lshl_add_u64 v[50:51], v[50:51], 2, v[18:19]
	v_lshl_add_u64 v[56:57], v[56:57], 2, v[18:19]
	v_lshl_add_u64 v[54:55], v[54:55], 2, v[18:19]
	v_lshl_add_u64 v[60:61], v[60:61], 2, v[18:19]
	v_lshl_add_u64 v[58:59], v[58:59], 2, v[18:19]
	v_lshl_add_u64 v[64:65], v[64:65], 2, v[18:19]
	v_lshl_add_u64 v[62:63], v[62:63], 2, v[18:19]
	v_lshl_add_u64 v[68:69], v[68:69], 2, v[18:19]
	v_lshl_add_u64 v[66:67], v[66:67], 2, v[18:19]
	global_load_dword v17, v[40:41], off nt
	global_load_dword v37, v[38:39], off nt
	global_load_dword v84, v[44:45], off nt
	global_load_dword v85, v[42:43], off nt
	global_load_dword v86, v[48:49], off nt
	global_load_dword v87, v[46:47], off nt
	global_load_dword v88, v[52:53], off nt
	global_load_dword v89, v[50:51], off nt
	global_load_dword v90, v[56:57], off nt
	global_load_dword v91, v[54:55], off nt
	global_load_dword v92, v[60:61], off nt
	global_load_dword v93, v[58:59], off nt
	global_load_dword v94, v[64:65], off nt
	global_load_dword v95, v[62:63], off nt
	global_load_dword v96, v[68:69], off nt
	global_load_dword v97, v[66:67], off nt
	s_add_i32 s5, s5, 16
	s_add_i32 s6, s6, 16
	v_mad_u64_u32 v[38:39], s[8:9], v11, s1, v[6:7]
	v_mad_u64_u32 v[40:41], s[8:9], v9, s1, v[6:7]
	v_mad_u64_u32 v[42:43], s[8:9], v71, s1, v[6:7]
	v_mad_u64_u32 v[44:45], s[8:9], v70, s1, v[6:7]
	v_mad_u64_u32 v[46:47], s[8:9], v73, s1, v[6:7]
	v_mad_u64_u32 v[48:49], s[8:9], v72, s1, v[6:7]
	v_mad_u64_u32 v[50:51], s[8:9], v75, s1, v[6:7]
	v_mad_u64_u32 v[52:53], s[8:9], v74, s1, v[6:7]
	v_mad_u64_u32 v[54:55], s[8:9], v77, s1, v[6:7]
	v_mad_u64_u32 v[56:57], s[8:9], v76, s1, v[6:7]
	v_mad_u64_u32 v[58:59], s[8:9], v79, s1, v[6:7]
	v_mad_u64_u32 v[60:61], s[8:9], v78, s1, v[6:7]
	v_mad_u64_u32 v[62:63], s[8:9], v81, s1, v[6:7]
	v_mad_u64_u32 v[64:65], s[8:9], v80, s1, v[6:7]
	v_mad_u64_u32 v[66:67], s[8:9], v83, s1, v[6:7]
	v_mad_u64_u32 v[68:69], s[8:9], v82, s1, v[6:7]
	s_lshl_b32 s8, s6, 1
	s_lshl_b32 s9, s5, 1
	v_or_b32_e32 v9, s8, v1
	v_or_b32_e32 v11, s9, v0
	s_add_i32 s10, s8, 4
	s_add_i32 s11, s9, 4
	s_add_i32 s12, s8, 8
	s_add_i32 s13, s9, 8
	s_add_i32 s14, s8, 12
	s_add_i32 s15, s9, 12
	s_add_i32 s16, s8, 16
	s_add_i32 s17, s9, 16
	s_add_i32 s18, s8, 20
	s_add_i32 s19, s9, 20
	s_add_i32 s20, s8, 24
	s_add_i32 s21, s9, 24
	s_add_i32 s8, s8, 28
	s_add_i32 s9, s9, 28
	v_add_u32_e32 v120, v9, v7
	v_add_u32_e32 v121, v11, v16
	v_or_b32_e32 v70, s10, v1
	v_or_b32_e32 v71, s11, v0
	v_or_b32_e32 v72, s12, v1
	v_or_b32_e32 v73, s13, v0
	v_or_b32_e32 v74, s14, v1
	v_or_b32_e32 v75, s15, v0
	v_or_b32_e32 v76, s16, v1
	v_or_b32_e32 v77, s17, v0
	v_or_b32_e32 v78, s18, v1
	v_or_b32_e32 v79, s19, v0
	v_or_b32_e32 v80, s20, v1
	v_or_b32_e32 v81, s21, v0
	v_or_b32_e32 v82, s8, v1
	v_or_b32_e32 v83, s9, v0
	v_ashrrev_i32_e32 v190, 31, v121
	v_ashrrev_i32_e32 v191, 31, v120
	v_mul_lo_u32 v122, v3, v120
	v_mad_u64_u32 v[186:187], s[8:9], v2, v120, 0
	v_mul_lo_u32 v120, v13, v121
	v_mad_u64_u32 v[188:189], s[8:9], v12, v121, 0
	v_add_u32_e32 v121, v70, v7
	v_add_u32_e32 v192, v71, v16
	v_add_u32_e32 v194, v72, v7
	v_add_u32_e32 v196, v73, v16
	v_add_u32_e32 v198, v74, v7
	v_add_u32_e32 v200, v75, v16
	v_add_u32_e32 v202, v76, v7
	v_add_u32_e32 v204, v77, v16
	v_add_u32_e32 v206, v78, v7
	v_add_u32_e32 v208, v79, v16
	v_add_u32_e32 v210, v80, v7
	v_add_u32_e32 v212, v81, v16
	v_add_u32_e32 v214, v82, v7
	v_add_u32_e32 v216, v83, v16
	v_mul_lo_u32 v123, v2, v191
	v_mul_lo_u32 v124, v12, v190
	v_ashrrev_i32_e32 v125, 31, v192
	v_ashrrev_i32_e32 v126, 31, v121
	v_ashrrev_i32_e32 v128, 31, v196
	v_ashrrev_i32_e32 v129, 31, v194
	v_ashrrev_i32_e32 v132, 31, v200
	v_ashrrev_i32_e32 v133, 31, v198
	v_ashrrev_i32_e32 v98, 31, v204
	v_ashrrev_i32_e32 v99, 31, v202
	v_ashrrev_i32_e32 v102, 31, v208
	v_ashrrev_i32_e32 v103, 31, v206
	v_ashrrev_i32_e32 v106, 31, v212
	v_ashrrev_i32_e32 v107, 31, v210
	v_ashrrev_i32_e32 v110, 31, v216
	v_ashrrev_i32_e32 v111, 31, v214
	v_mul_lo_u32 v127, v3, v121
	v_mad_u64_u32 v[190:191], s[8:9], v2, v121, 0
	v_mul_lo_u32 v121, v13, v192
	v_mad_u64_u32 v[192:193], s[8:9], v12, v192, 0
	v_mul_lo_u32 v130, v3, v194
	v_mad_u64_u32 v[194:195], s[8:9], v2, v194, 0
	v_mul_lo_u32 v131, v13, v196
	v_mad_u64_u32 v[196:197], s[8:9], v12, v196, 0
	v_mul_lo_u32 v134, v3, v198
	v_mad_u64_u32 v[198:199], s[8:9], v2, v198, 0
	v_mul_lo_u32 v135, v13, v200
	v_mad_u64_u32 v[200:201], s[8:9], v12, v200, 0
	v_mul_lo_u32 v100, v3, v202
	v_mad_u64_u32 v[202:203], s[8:9], v2, v202, 0
	v_mul_lo_u32 v101, v13, v204
	v_mad_u64_u32 v[204:205], s[8:9], v12, v204, 0
	v_mul_lo_u32 v104, v3, v206
	v_mad_u64_u32 v[206:207], s[8:9], v2, v206, 0
	v_mul_lo_u32 v105, v13, v208
	v_mad_u64_u32 v[208:209], s[8:9], v12, v208, 0
	v_mul_lo_u32 v108, v3, v210
	v_mad_u64_u32 v[210:211], s[8:9], v2, v210, 0
	v_mul_lo_u32 v109, v13, v212
	v_mad_u64_u32 v[212:213], s[8:9], v12, v212, 0
	v_mul_lo_u32 v112, v3, v214
	v_mad_u64_u32 v[214:215], s[8:9], v2, v214, 0
	v_mul_lo_u32 v113, v13, v216
	v_mad_u64_u32 v[216:217], s[8:9], v12, v216, 0
	v_add3_u32 v187, v187, v123, v122
	v_add3_u32 v189, v189, v124, v120
	v_mul_lo_u32 v120, v2, v126
	v_mul_lo_u32 v122, v12, v125
	v_mul_lo_u32 v123, v2, v129
	v_mul_lo_u32 v124, v12, v128
	v_mul_lo_u32 v125, v2, v133
	v_mul_lo_u32 v126, v12, v132
	v_mul_lo_u32 v128, v2, v99
	v_mul_lo_u32 v129, v12, v98
	v_mul_lo_u32 v132, v2, v103
	v_mul_lo_u32 v133, v12, v102
	v_mul_lo_u32 v98, v2, v107
	v_mul_lo_u32 v99, v12, v106
	v_mul_lo_u32 v102, v2, v111
	v_mul_lo_u32 v103, v12, v110
	v_lshl_add_u64 v[188:189], v[188:189], 2, v[18:19]
	v_add3_u32 v191, v191, v120, v127
	v_add3_u32 v193, v193, v122, v121
	v_add3_u32 v195, v195, v123, v130
	v_add3_u32 v197, v197, v124, v131
	v_add3_u32 v199, v199, v125, v134
	v_add3_u32 v201, v201, v126, v135
	v_add3_u32 v203, v203, v128, v100
	v_add3_u32 v205, v205, v129, v101
	v_add3_u32 v207, v207, v132, v104
	v_add3_u32 v209, v209, v133, v105
	v_add3_u32 v211, v211, v98, v108
	v_add3_u32 v213, v213, v99, v109
	v_add3_u32 v215, v215, v102, v112
	v_add3_u32 v217, v217, v103, v113
	v_lshl_add_u64 v[186:187], v[186:187], 2, v[18:19]
	v_lshl_add_u64 v[192:193], v[192:193], 2, v[18:19]
	v_lshl_add_u64 v[190:191], v[190:191], 2, v[18:19]
	v_lshl_add_u64 v[196:197], v[196:197], 2, v[18:19]
	v_lshl_add_u64 v[194:195], v[194:195], 2, v[18:19]
	v_lshl_add_u64 v[200:201], v[200:201], 2, v[18:19]
	v_lshl_add_u64 v[198:199], v[198:199], 2, v[18:19]
	v_lshl_add_u64 v[204:205], v[204:205], 2, v[18:19]
	v_lshl_add_u64 v[202:203], v[202:203], 2, v[18:19]
	v_lshl_add_u64 v[208:209], v[208:209], 2, v[18:19]
	v_lshl_add_u64 v[206:207], v[206:207], 2, v[18:19]
	v_lshl_add_u64 v[212:213], v[212:213], 2, v[18:19]
	v_lshl_add_u64 v[210:211], v[210:211], 2, v[18:19]
	v_lshl_add_u64 v[216:217], v[216:217], 2, v[18:19]
	v_lshl_add_u64 v[214:215], v[214:215], 2, v[18:19]
	global_load_dword v120, v[188:189], off nt
	global_load_dword v121, v[186:187], off nt
	global_load_dword v122, v[192:193], off nt
	global_load_dword v123, v[190:191], off nt
	global_load_dword v124, v[196:197], off nt
	global_load_dword v125, v[194:195], off nt
	global_load_dword v126, v[200:201], off nt
	global_load_dword v127, v[198:199], off nt
	global_load_dword v128, v[204:205], off nt
	global_load_dword v129, v[202:203], off nt
	global_load_dword v130, v[208:209], off nt
	global_load_dword v131, v[206:207], off nt
	global_load_dword v132, v[212:213], off nt
	global_load_dword v133, v[210:211], off nt
	global_load_dword v134, v[216:217], off nt
	global_load_dword v135, v[214:215], off nt
	s_add_i32 s5, s5, 16
	s_add_i32 s6, s6, 16
	s_mov_b32 s7, 0
	v_mad_u64_u32 v[186:187], s[8:9], v11, s1, v[6:7]
	v_mad_u64_u32 v[188:189], s[8:9], v9, s1, v[6:7]
	v_mad_u64_u32 v[190:191], s[8:9], v71, s1, v[6:7]
	v_mad_u64_u32 v[192:193], s[8:9], v70, s1, v[6:7]
	v_mad_u64_u32 v[194:195], s[8:9], v73, s1, v[6:7]
	v_mad_u64_u32 v[196:197], s[8:9], v72, s1, v[6:7]
	v_mad_u64_u32 v[198:199], s[8:9], v75, s1, v[6:7]
	v_mad_u64_u32 v[200:201], s[8:9], v74, s1, v[6:7]
	v_mad_u64_u32 v[202:203], s[8:9], v77, s1, v[6:7]
	v_mad_u64_u32 v[204:205], s[8:9], v76, s1, v[6:7]
	v_mad_u64_u32 v[206:207], s[8:9], v79, s1, v[6:7]
	v_mad_u64_u32 v[208:209], s[8:9], v78, s1, v[6:7]
	v_mad_u64_u32 v[210:211], s[8:9], v81, s1, v[6:7]
	v_mad_u64_u32 v[212:213], s[8:9], v80, s1, v[6:7]
	v_mad_u64_u32 v[214:215], s[8:9], v83, s1, v[6:7]
	v_mad_u64_u32 v[216:217], s[8:9], v82, s1, v[6:7]
	s_waitcnt vmcnt(31)
	ds_write_b32 v38, v17
	s_waitcnt vmcnt(30)
	ds_write_b32 v40, v37
	s_waitcnt vmcnt(29)
	ds_write_b32 v42, v84
	s_waitcnt vmcnt(28)
	ds_write_b32 v44, v85
	s_waitcnt vmcnt(27)
	ds_write_b32 v46, v86
	s_waitcnt vmcnt(26)
	ds_write_b32 v48, v87
	s_waitcnt vmcnt(25)
	ds_write_b32 v50, v88
	s_waitcnt vmcnt(24)
	ds_write_b32 v52, v89
	s_waitcnt vmcnt(23)
	ds_write_b32 v54, v90
	s_waitcnt vmcnt(22)
	ds_write_b32 v56, v91
	s_waitcnt vmcnt(21)
	ds_write_b32 v58, v92
	s_waitcnt vmcnt(20)
	ds_write_b32 v60, v93
	s_waitcnt vmcnt(19)
	ds_write_b32 v62, v94
	s_waitcnt vmcnt(18)
	ds_write_b32 v64, v95
	s_waitcnt vmcnt(17)
	ds_write_b32 v66, v96
	s_waitcnt vmcnt(16)
	ds_write_b32 v68, v97
	s_waitcnt vmcnt(15)
	ds_write_b32 v186, v120
	s_waitcnt vmcnt(14)
	ds_write_b32 v188, v121
	s_waitcnt vmcnt(13)
	ds_write_b32 v190, v122
	s_waitcnt vmcnt(12)
	ds_write_b32 v192, v123
	s_waitcnt vmcnt(11)
	ds_write_b32 v194, v124
	s_waitcnt vmcnt(10)
	ds_write_b32 v196, v125
	s_waitcnt vmcnt(9)
	ds_write_b32 v198, v126
	s_waitcnt vmcnt(8)
	ds_write_b32 v200, v127
	s_waitcnt vmcnt(7)
	ds_write_b32 v202, v128
	s_waitcnt vmcnt(6)
	ds_write_b32 v204, v129
	s_waitcnt vmcnt(5)
	ds_write_b32 v206, v130
	s_waitcnt vmcnt(4)
	ds_write_b32 v208, v131
	s_waitcnt vmcnt(3)
	ds_write_b32 v210, v132
	s_waitcnt vmcnt(2)
	ds_write_b32 v212, v133
	s_waitcnt vmcnt(1)
	ds_write_b32 v214, v134
	s_waitcnt vmcnt(0)
	ds_write_b32 v216, v135
	s_waitcnt lgkmcnt(0)
	v_ashrrev_i32_e32 v17, 31, v16
	v_lshl_add_u64 v[2:3], v[16:17], 1, v[14:15]
	ds_read2_b32 v[16:17], v20 offset0:33 offset1:41
	ds_read2_b32 v[18:19], v20 offset1:8
	ds_read2_b32 v[38:39], v20 offset0:66 offset1:74
	ds_read2_b32 v[40:41], v20 offset0:99 offset1:107
	ds_read2_b32 v[42:43], v20 offset0:132 offset1:140
	ds_read2_b32 v[44:45], v20 offset0:165 offset1:173
	ds_read2_b32 v[46:47], v20 offset0:198 offset1:206
	ds_read2_b32 v[48:49], v20 offset0:231 offset1:239
	v_or_b32_e32 v7, v4, v185
	v_ashrrev_i32_e32 v9, 31, v4
	v_mov_b32_e32 v11, v5
	v_mul_lo_u32 v9, v9, v36
	v_mad_u64_u32 v[50:51], s[6:7], v7, v36, 0
	v_lshl_add_u64 v[2:3], v[2:3], 0, v[10:11]
	v_add_u32_e32 v51, v51, v9
	s_waitcnt lgkmcnt(6)
	v_cvt_pk_bf16_f32 v12, v18, v16
	s_waitcnt lgkmcnt(4)
	v_cvt_pk_bf16_f32 v13, v38, v40
	s_waitcnt lgkmcnt(2)
	v_cvt_pk_bf16_f32 v14, v42, v44
	s_waitcnt lgkmcnt(0)
	v_cvt_pk_bf16_f32 v15, v46, v48
	v_lshl_add_u64 v[50:51], v[50:51], 1, v[2:3]
	global_store_dwordx4 v[50:51], v[12:15], off sc1
	v_or_b32_e32 v7, v4, v21
	s_add_i32 s5, s0, 0x80
	v_cvt_pk_bf16_f32 v12, v19, v17
	v_cvt_pk_bf16_f32 v13, v39, v41
	v_cvt_pk_bf16_f32 v14, v43, v45
	v_cvt_pk_bf16_f32 v15, v47, v49
	v_mad_u64_u32 v[16:17], s[6:7], v7, v36, 0
	ds_read2_b32 v[18:19], v20 offset0:16 offset1:24
	ds_read2_b32 v[38:39], v20 offset0:49 offset1:57
	ds_read2_b32 v[40:41], v20 offset0:82 offset1:90
	ds_read2_b32 v[42:43], v20 offset0:115 offset1:123
	ds_read2_b32 v[44:45], v20 offset0:148 offset1:156
	ds_read2_b32 v[46:47], v20 offset0:181 offset1:189
	ds_read2_b32 v[48:49], v20 offset0:214 offset1:222
	ds_read2_b32 v[50:51], v20 offset0:247 offset1:255
	v_add_u32_e32 v17, v17, v9
	v_lshl_add_u64 v[16:17], v[16:17], 1, v[2:3]
	v_or_b32_e32 v7, v4, v22
	global_store_dwordx4 v[16:17], v[12:15], off sc1
	v_mad_u64_u32 v[16:17], s[6:7], v7, v36, 0
	v_add_u32_e32 v17, v17, v9
	s_waitcnt lgkmcnt(6)
	v_cvt_pk_bf16_f32 v12, v18, v38
	s_waitcnt lgkmcnt(4)
	v_cvt_pk_bf16_f32 v13, v40, v42
	s_waitcnt lgkmcnt(2)
	v_cvt_pk_bf16_f32 v14, v44, v46
	s_waitcnt lgkmcnt(0)
	v_cvt_pk_bf16_f32 v15, v48, v50
	v_lshl_add_u64 v[16:17], v[16:17], 1, v[2:3]
	v_or_b32_e32 v4, v4, v23
	global_store_dwordx4 v[16:17], v[12:15], off sc1
	v_mad_u64_u32 v[16:17], s[6:7], v4, v36, 0
	v_add_u32_e32 v17, v17, v9
	v_cvt_pk_bf16_f32 v12, v19, v39
	v_cvt_pk_bf16_f32 v13, v41, v43
	v_cvt_pk_bf16_f32 v14, v45, v47
	v_cvt_pk_bf16_f32 v15, v49, v51
	v_lshl_add_u64 v[2:3], v[16:17], 1, v[2:3]
	global_store_dwordx4 v[2:3], v[12:15], off sc1
	s_waitcnt lgkmcnt(0)
	s_cmpk_gt_i32 s0, 0x28f
	s_mov_b32 s0, s5
	s_cbranch_scc0 .Lgu0e_BB0_1019

.Lgu0e_skip:
	s_cmpk_lt_u32 s78, 0x80
	s_cbranch_scc1 .Lgu0e_done
	s_waitcnt vmcnt(0)
	s_barrier
	s_mov_b64 s[100:101], exec
	v_readlane_b32 s98, v219, 25
	v_readlane_b32 s99, v219, 26
	s_nop 1
	s_and_b64 s[98:99], s[100:101], s[98:99]
	s_mov_b64 exec, s[98:99]
	s_cbranch_execz .Lgu0e_noat
	v_readlane_b32 s98, v219, 27
	v_readlane_b32 s99, v219, 28
	v_mov_b32_e32 v0, 1
	v_mov_b32_e32 v1, 0x11c0
	s_nop 3
	global_atomic_add v1, v0, s[98:99]

.Lgb7_spin2:
	global_load_dword v2, v1, s[0:1] sc1
	s_waitcnt vmcnt(0)
	v_readfirstlane_b32 s13, v2
	s_nop 1
	s_cmp_ge_u32 s13, 128
	s_cbranch_scc1 .Lgb7_done2
	s_sleep 4
	s_add_i32 s15, s15, 1
	s_cmp_lt_u32 s15, 0x200000
	s_cbranch_scc1 .Lgb7_spin2
